# weight-convert loops of the prologue phase: later groups loads issued up front as L2 warm-up so serialized waits hit L2
# baseline (speedup 1.0000x reference)
; __device__ __forceinline__ void transpose_item(const float* W, int K, int Nsrc, bf16_t* WT, int dst_n0, int src_n0, int nvalid, const float* kgain, int k0, LAS float* scr, int lane) {
;     ...
; #pragma unroll 32
;     for (int i = 0; i < 32; ++i) { const int kk = 2 * i + (lane >> 5);
;         float v = (srcn < nvalid) ? W[(size_t)(k0 + kk) * Nsrc + srcn] : 0.f;
;         if (kgain) v *= kgain[k0 + kk];
;         scr[kk * 33 + (lane & 31)] = v; }
; __device__ __forceinline__ void convert_group(const Frame& F, const float* W, int nl, int K, int Nsrc, int Ndst, bf16_t* WT, int kind, const float* kgain, int gain_stride) {
;     ...
;     for (int it = F.gw; it < total; it += F.NGW) {
;         const int l = it / per, r = it % per, kb = r / nblk, nb = r % nblk, dn0 = nb * 32;
;         int sn0 = dn0;
;         if (kind == 1) { const int j = dn0 >> 8, i0 = dn0 & 255; sn0 = (i0 < 128) ? (128 * j + i0) : (D_FF + 128 * j + i0 - 128); }
;         transpose_item(W + (size_t)l * K * Nsrc, K, Nsrc, WT + (size_t)l * Ndst * K, dn0, sn0, Nsrc, kgain ? kgain + l * gain_stride : nullptr, kb * 64, scr, lane_l);
.LBB0_568:
	s_mul_hi_i32 s6, s12, 0x38e38e39
	s_lshr_b32 s7, s6, 31
	s_ashr_i32 s14, s6, 8
	s_add_i32 s14, s14, s7
	s_mul_i32 s6, s14, 0xfffffb80
	s_add_i32 s6, s12, s6
	s_mul_i32 s7, s6, 0xe39
	s_lshr_b32 s8, s7, 31
	s_ashr_i32 s15, s7, 18
	s_add_i32 s15, s15, s8
	s_mul_i32 s7, s15, 0x48
	s_sub_i32 s6, s6, s7
	s_sext_i32_i16 s6, s6
	s_lshl_b32 s13, s6, 5
	s_mul_i32 s7, s14, 0x8a8000
	s_mul_hi_i32 s6, s14, 0x8a8000
	s_add_u32 s10, s4, s7
	s_addc_u32 s11, s5, s6
	v_or_b32_e32 v0, s13, v2
	s_movk_i32 s6, 0x8a7
	v_cmp_lt_i32_e32 vcc, s6, v0
	s_and_saveexec_b64 s[6:7], vcc
	s_xor_b64 s[6:7], exec, s[6:7]
	ds_write2_b32 v43, v165, v165 offset1:66
	s_or_saveexec_b64 s[8:9], s[6:7]
	v_ashrrev_i32_e32 v1, 31, v0
	s_lshl_b32 s6, s15, 6
	v_lshl_add_u64 v[0:1], v[0:1], 2, s[10:11]
	v_mov_b32_e32 v46, 0
	v_mov_b32_e32 v47, 0
	s_xor_b64 exec, exec, s[8:9]
	s_cbranch_execz .LBB0_572
	v_or_b32_e32 v46, s6, v8
	v_or_b32_e32 v48, s6, v9
	v_mul_i32_i24_e32 v46, 0x8a8, v46
	v_mul_i32_i24_e32 v48, 0x8a8, v48
	v_or_b32_e32 v50, s6, v10
	v_or_b32_e32 v52, s6, v11
	v_ashrrev_i32_e32 v47, 31, v46
	v_ashrrev_i32_e32 v49, 31, v48
	v_mul_i32_i24_e32 v50, 0x8a8, v50
	v_mul_i32_i24_e32 v52, 0x8a8, v52
	v_lshl_add_u64 v[46:47], v[46:47], 2, v[0:1]
	v_lshl_add_u64 v[48:49], v[48:49], 2, v[0:1]
	v_ashrrev_i32_e32 v51, 31, v50
	v_ashrrev_i32_e32 v53, 31, v52
	v_lshl_add_u64 v[50:51], v[50:51], 2, v[0:1]
	v_lshl_add_u64 v[52:53], v[52:53], 2, v[0:1]
	global_load_dword v240, v[46:47], off
	global_load_dword v240, v[48:49], off
	global_load_dword v240, v[50:51], off
	global_load_dword v240, v[52:53], off
	v_or_b32_e32 v46, s6, v12
	v_or_b32_e32 v48, s6, v13
	v_mul_i32_i24_e32 v46, 0x8a8, v46
	v_mul_i32_i24_e32 v48, 0x8a8, v48
	v_or_b32_e32 v50, s6, v14
	v_or_b32_e32 v52, s6, v15
	v_ashrrev_i32_e32 v47, 31, v46
	v_ashrrev_i32_e32 v49, 31, v48
	v_mul_i32_i24_e32 v50, 0x8a8, v50
	v_mul_i32_i24_e32 v52, 0x8a8, v52
	v_lshl_add_u64 v[46:47], v[46:47], 2, v[0:1]
	v_lshl_add_u64 v[48:49], v[48:49], 2, v[0:1]
	v_ashrrev_i32_e32 v51, 31, v50
	v_ashrrev_i32_e32 v53, 31, v52
	v_lshl_add_u64 v[50:51], v[50:51], 2, v[0:1]
	v_lshl_add_u64 v[52:53], v[52:53], 2, v[0:1]
	global_load_dword v240, v[46:47], off
	global_load_dword v240, v[48:49], off
	global_load_dword v240, v[50:51], off
	global_load_dword v240, v[52:53], off
	v_or_b32_e32 v47, s6, v16
	v_mul_i32_i24_e32 v48, 0x8a8, v47
	v_or_b32_e32 v47, s6, v17
	v_mul_i32_i24_e32 v50, 0x8a8, v47
	v_or_b32_e32 v47, s6, v18
	v_mul_i32_i24_e32 v52, 0x8a8, v47
	v_or_b32_e32 v47, s6, v19
	v_ashrrev_i32_e32 v49, 31, v48
	v_ashrrev_i32_e32 v51, 31, v50
	v_mul_i32_i24_e32 v54, 0x8a8, v47
	v_lshl_add_u64 v[48:49], v[48:49], 2, v[0:1]
	v_lshl_add_u64 v[50:51], v[50:51], 2, v[0:1]
	v_ashrrev_i32_e32 v53, 31, v52
	v_ashrrev_i32_e32 v55, 31, v54
	v_lshl_add_u64 v[52:53], v[52:53], 2, v[0:1]
	v_lshl_add_u64 v[54:55], v[54:55], 2, v[0:1]
	global_load_dword v240, v[48:49], off
	global_load_dword v240, v[50:51], off
	global_load_dword v240, v[52:53], off
	global_load_dword v240, v[54:55], off
	v_or_b32_e32 v47, s6, v20
	v_mul_i32_i24_e32 v48, 0x8a8, v47
	v_or_b32_e32 v47, s6, v21
	v_mul_i32_i24_e32 v50, 0x8a8, v47
	v_or_b32_e32 v47, s6, v22
	v_mul_i32_i24_e32 v52, 0x8a8, v47
	v_or_b32_e32 v47, s6, v23
	v_ashrrev_i32_e32 v49, 31, v48
	v_ashrrev_i32_e32 v51, 31, v50
	v_mul_i32_i24_e32 v54, 0x8a8, v47
	v_lshl_add_u64 v[48:49], v[48:49], 2, v[0:1]
	v_lshl_add_u64 v[50:51], v[50:51], 2, v[0:1]
	v_ashrrev_i32_e32 v53, 31, v52
	v_ashrrev_i32_e32 v55, 31, v54
	v_lshl_add_u64 v[52:53], v[52:53], 2, v[0:1]
	v_lshl_add_u64 v[54:55], v[54:55], 2, v[0:1]
	global_load_dword v240, v[48:49], off
	global_load_dword v240, v[50:51], off
	global_load_dword v240, v[52:53], off
	global_load_dword v240, v[54:55], off
	v_or_b32_e32 v47, s6, v24
	v_mul_i32_i24_e32 v48, 0x8a8, v47
	v_or_b32_e32 v47, s6, v25
	v_mul_i32_i24_e32 v50, 0x8a8, v47
	v_or_b32_e32 v47, s6, v26
	v_mul_i32_i24_e32 v52, 0x8a8, v47
	v_or_b32_e32 v47, s6, v27
	v_ashrrev_i32_e32 v49, 31, v48
	v_ashrrev_i32_e32 v51, 31, v50
	v_mul_i32_i24_e32 v54, 0x8a8, v47
	v_lshl_add_u64 v[48:49], v[48:49], 2, v[0:1]
	v_lshl_add_u64 v[50:51], v[50:51], 2, v[0:1]
	v_ashrrev_i32_e32 v53, 31, v52
	v_ashrrev_i32_e32 v55, 31, v54
	v_lshl_add_u64 v[52:53], v[52:53], 2, v[0:1]
	v_lshl_add_u64 v[54:55], v[54:55], 2, v[0:1]
	global_load_dword v240, v[48:49], off
	global_load_dword v240, v[50:51], off
	global_load_dword v240, v[52:53], off
	global_load_dword v240, v[54:55], off
	v_or_b32_e32 v47, s6, v28
	v_mul_i32_i24_e32 v48, 0x8a8, v47
	v_or_b32_e32 v47, s6, v29
	v_mul_i32_i24_e32 v50, 0x8a8, v47
	v_or_b32_e32 v47, s6, v30
	v_mul_i32_i24_e32 v52, 0x8a8, v47
	v_or_b32_e32 v47, s6, v31
	v_ashrrev_i32_e32 v49, 31, v48
	v_ashrrev_i32_e32 v51, 31, v50
	v_mul_i32_i24_e32 v54, 0x8a8, v47
	v_lshl_add_u64 v[48:49], v[48:49], 2, v[0:1]
	v_lshl_add_u64 v[50:51], v[50:51], 2, v[0:1]
	v_ashrrev_i32_e32 v53, 31, v52
	v_ashrrev_i32_e32 v55, 31, v54
	v_lshl_add_u64 v[52:53], v[52:53], 2, v[0:1]
	v_lshl_add_u64 v[54:55], v[54:55], 2, v[0:1]
	global_load_dword v240, v[48:49], off
	global_load_dword v240, v[50:51], off
	global_load_dword v240, v[52:53], off
	global_load_dword v240, v[54:55], off
	v_or_b32_e32 v47, s6, v32
	v_mul_i32_i24_e32 v48, 0x8a8, v47
	v_or_b32_e32 v47, s6, v33
	v_mul_i32_i24_e32 v50, 0x8a8, v47
	v_or_b32_e32 v47, s6, v34
	v_mul_i32_i24_e32 v52, 0x8a8, v47
	v_or_b32_e32 v47, s6, v35
	v_ashrrev_i32_e32 v49, 31, v48
	v_ashrrev_i32_e32 v51, 31, v50
	v_mul_i32_i24_e32 v54, 0x8a8, v47
	v_lshl_add_u64 v[48:49], v[48:49], 2, v[0:1]
	v_lshl_add_u64 v[50:51], v[50:51], 2, v[0:1]
	v_ashrrev_i32_e32 v53, 31, v52
	v_ashrrev_i32_e32 v55, 31, v54
	v_lshl_add_u64 v[52:53], v[52:53], 2, v[0:1]
	v_lshl_add_u64 v[54:55], v[54:55], 2, v[0:1]
	global_load_dword v240, v[48:49], off
	global_load_dword v240, v[50:51], off
	global_load_dword v240, v[52:53], off
	global_load_dword v240, v[54:55], off
	v_or_b32_e32 v46, s6, v3
	v_or_b32_e32 v48, s6, v4
	v_mul_i32_i24_e32 v46, 0x8a8, v46
	v_mul_i32_i24_e32 v48, 0x8a8, v48
	v_or_b32_e32 v50, s6, v5
	v_or_b32_e32 v52, s6, v7
	v_ashrrev_i32_e32 v47, 31, v46
	v_ashrrev_i32_e32 v49, 31, v48
	v_mul_i32_i24_e32 v50, 0x8a8, v50
	v_mul_i32_i24_e32 v52, 0x8a8, v52
	v_lshl_add_u64 v[46:47], v[46:47], 2, v[0:1]
	v_lshl_add_u64 v[48:49], v[48:49], 2, v[0:1]
	v_ashrrev_i32_e32 v51, 31, v50
	v_ashrrev_i32_e32 v53, 31, v52
	v_lshl_add_u64 v[50:51], v[50:51], 2, v[0:1]
	v_lshl_add_u64 v[52:53], v[52:53], 2, v[0:1]
	global_load_dword v54, v[46:47], off
	s_nop 0
	global_load_dword v48, v[48:49], off
	s_nop 0
	global_load_dword v46, v[50:51], off
	global_load_dword v47, v[52:53], off
	s_waitcnt vmcnt(2)
	ds_write2_b32 v43, v54, v48 offset1:66

; __device__ __forceinline__ void transpose_item(const float* W, int K, int Nsrc, bf16_t* WT, int dst_n0, int src_n0, int nvalid, const float* kgain, int k0, LAS float* scr, int lane) {
;     ...
; #pragma unroll 32
;     for (int i = 0; i < 32; ++i) { const int kk = 2 * i + (lane >> 5);
;         float v = (srcn < nvalid) ? W[(size_t)(k0 + kk) * Nsrc + srcn] : 0.f;
;         if (kgain) v *= kgain[k0 + kk];
;         scr[kk * 33 + (lane & 31)] = v; }
; __device__ __forceinline__ void convert_group(const Frame& F, const float* W, int nl, int K, int Nsrc, int Ndst, bf16_t* WT, int kind, const float* kgain, int gain_stride) {
;     ...
;     for (int it = F.gw; it < total; it += F.NGW) {
;         const int l = it / per, r = it % per, kb = r / nblk, nb = r % nblk, dn0 = nb * 32;
;         int sn0 = dn0;
;         if (kind == 1) { const int j = dn0 >> 8, i0 = dn0 & 255; sn0 = (i0 < 128) ? (128 * j + i0) : (D_FF + 128 * j + i0 - 128); }
;         transpose_item(W + (size_t)l * K * Nsrc, K, Nsrc, WT + (size_t)l * Ndst * K, dn0, sn0, Nsrc, kgain ? kgain + l * gain_stride : nullptr, kb * 64, scr, lane_l);
.LBB0_639:
	s_mul_hi_i32 s6, s24, 0x38e38e39
	s_lshr_b32 s7, s6, 31
	s_ashr_i32 s11, s6, 5
	s_add_i32 s11, s11, s7
	s_mul_i32 s6, s11, 0xffffff70
	s_add_i32 s6, s24, s6
	s_mul_i32 s7, s6, 0x2aab
	s_lshr_b32 s8, s7, 31
	s_ashr_i32 s7, s7, 18
	s_add_i32 s10, s7, s8
	s_mul_i32 s7, s10, 24
	s_sub_i32 s6, s6, s7
	s_sext_i32_i16 s6, s6
	s_mul_hi_i32 s17, s11, 0x48000
	s_mul_i32 s16, s11, 0x48000
	s_lshl_b32 s25, s6, 5
	s_lshl_b64 s[6:7], s[16:17], 2
	s_add_u32 s8, s14, s6
	v_or_b32_e32 v2, s25, v7
	s_addc_u32 s9, s15, s7
	s_lshl_b32 s10, s10, 6
	s_movk_i32 s6, 0x300
	v_ashrrev_i32_e32 v3, 31, v2
	v_cmp_gt_i32_e64 s[6:7], s6, v2
	v_lshl_add_u64 v[2:3], v[2:3], 2, s[8:9]
	v_mov_b32_e32 v45, 0
	v_or_b32_e32 v4, s10, v0
	s_and_saveexec_b64 s[8:9], s[6:7]
	s_cbranch_execz .LBB0_641
	v_or_b32_e32 v100, s10, v8
	v_mul_i32_i24_e32 v100, 0x300, v100
	v_ashrrev_i32_e32 v101, 31, v100
	v_lshl_add_u64 v[100:101], v[100:101], 2, v[2:3]
	global_load_dword v240, v[100:101], off
	v_or_b32_e32 v100, s10, v9
	v_mul_i32_i24_e32 v100, 0x300, v100
	v_ashrrev_i32_e32 v101, 31, v100
	v_lshl_add_u64 v[100:101], v[100:101], 2, v[2:3]
	global_load_dword v240, v[100:101], off
	v_or_b32_e32 v100, s10, v10
	v_mul_i32_i24_e32 v100, 0x300, v100
	v_ashrrev_i32_e32 v101, 31, v100
	v_lshl_add_u64 v[100:101], v[100:101], 2, v[2:3]
	global_load_dword v240, v[100:101], off
	v_or_b32_e32 v100, s10, v11
	v_mul_i32_i24_e32 v100, 0x300, v100
	v_ashrrev_i32_e32 v101, 31, v100
	v_lshl_add_u64 v[100:101], v[100:101], 2, v[2:3]
	global_load_dword v240, v[100:101], off
	v_or_b32_e32 v100, s10, v12
	v_mul_i32_i24_e32 v100, 0x300, v100
	v_ashrrev_i32_e32 v101, 31, v100
	v_lshl_add_u64 v[100:101], v[100:101], 2, v[2:3]
	global_load_dword v240, v[100:101], off
	v_or_b32_e32 v100, s10, v13
	v_mul_i32_i24_e32 v100, 0x300, v100
	v_ashrrev_i32_e32 v101, 31, v100
	v_lshl_add_u64 v[100:101], v[100:101], 2, v[2:3]
	global_load_dword v240, v[100:101], off
	v_or_b32_e32 v100, s10, v14
	v_mul_i32_i24_e32 v100, 0x300, v100
	v_ashrrev_i32_e32 v101, 31, v100
	v_lshl_add_u64 v[100:101], v[100:101], 2, v[2:3]
	global_load_dword v240, v[100:101], off
	v_or_b32_e32 v100, s10, v15
	v_mul_i32_i24_e32 v100, 0x300, v100
	v_ashrrev_i32_e32 v101, 31, v100
	v_lshl_add_u64 v[100:101], v[100:101], 2, v[2:3]
	global_load_dword v240, v[100:101], off
	v_or_b32_e32 v100, s10, v16
	v_mul_i32_i24_e32 v100, 0x300, v100
	v_ashrrev_i32_e32 v101, 31, v100
	v_lshl_add_u64 v[100:101], v[100:101], 2, v[2:3]
	global_load_dword v240, v[100:101], off
	v_or_b32_e32 v100, s10, v17
	v_mul_i32_i24_e32 v100, 0x300, v100
	v_ashrrev_i32_e32 v101, 31, v100
	v_lshl_add_u64 v[100:101], v[100:101], 2, v[2:3]
	global_load_dword v240, v[100:101], off
	v_or_b32_e32 v100, s10, v18
	v_mul_i32_i24_e32 v100, 0x300, v100
	v_ashrrev_i32_e32 v101, 31, v100
	v_lshl_add_u64 v[100:101], v[100:101], 2, v[2:3]
	global_load_dword v240, v[100:101], off
	v_or_b32_e32 v100, s10, v19
	v_mul_i32_i24_e32 v100, 0x300, v100
	v_ashrrev_i32_e32 v101, 31, v100
	v_lshl_add_u64 v[100:101], v[100:101], 2, v[2:3]
	global_load_dword v240, v[100:101], off
	v_or_b32_e32 v100, s10, v20
	v_mul_i32_i24_e32 v100, 0x300, v100
	v_ashrrev_i32_e32 v101, 31, v100
	v_lshl_add_u64 v[100:101], v[100:101], 2, v[2:3]
	global_load_dword v240, v[100:101], off
	v_or_b32_e32 v100, s10, v21
	v_mul_i32_i24_e32 v100, 0x300, v100
	v_ashrrev_i32_e32 v101, 31, v100
	v_lshl_add_u64 v[100:101], v[100:101], 2, v[2:3]
	global_load_dword v240, v[100:101], off
	v_or_b32_e32 v100, s10, v22
	v_mul_i32_i24_e32 v100, 0x300, v100
	v_ashrrev_i32_e32 v101, 31, v100
	v_lshl_add_u64 v[100:101], v[100:101], 2, v[2:3]
	global_load_dword v240, v[100:101], off
	v_or_b32_e32 v100, s10, v23
	v_mul_i32_i24_e32 v100, 0x300, v100
	v_ashrrev_i32_e32 v101, 31, v100
	v_lshl_add_u64 v[100:101], v[100:101], 2, v[2:3]
	global_load_dword v240, v[100:101], off
	v_or_b32_e32 v100, s10, v24
	v_mul_i32_i24_e32 v100, 0x300, v100
	v_ashrrev_i32_e32 v101, 31, v100
	v_lshl_add_u64 v[100:101], v[100:101], 2, v[2:3]
	global_load_dword v240, v[100:101], off
	v_or_b32_e32 v100, s10, v25
	v_mul_i32_i24_e32 v100, 0x300, v100
	v_ashrrev_i32_e32 v101, 31, v100
	v_lshl_add_u64 v[100:101], v[100:101], 2, v[2:3]
	global_load_dword v240, v[100:101], off
	v_or_b32_e32 v100, s10, v26
	v_mul_i32_i24_e32 v100, 0x300, v100
	v_ashrrev_i32_e32 v101, 31, v100
	v_lshl_add_u64 v[100:101], v[100:101], 2, v[2:3]
	global_load_dword v240, v[100:101], off
	v_or_b32_e32 v100, s10, v27
	v_mul_i32_i24_e32 v100, 0x300, v100
	v_ashrrev_i32_e32 v101, 31, v100
	v_lshl_add_u64 v[100:101], v[100:101], 2, v[2:3]
	global_load_dword v240, v[100:101], off
	v_or_b32_e32 v100, s10, v28
	v_mul_i32_i24_e32 v100, 0x300, v100
	v_ashrrev_i32_e32 v101, 31, v100
	v_lshl_add_u64 v[100:101], v[100:101], 2, v[2:3]
	global_load_dword v240, v[100:101], off
	v_or_b32_e32 v100, s10, v29
	v_mul_i32_i24_e32 v100, 0x300, v100
	v_ashrrev_i32_e32 v101, 31, v100
	v_lshl_add_u64 v[100:101], v[100:101], 2, v[2:3]
	global_load_dword v240, v[100:101], off
	v_or_b32_e32 v100, s10, v30
	v_mul_i32_i24_e32 v100, 0x300, v100
	v_ashrrev_i32_e32 v101, 31, v100
	v_lshl_add_u64 v[100:101], v[100:101], 2, v[2:3]
	global_load_dword v240, v[100:101], off
	v_or_b32_e32 v100, s10, v31
	v_mul_i32_i24_e32 v100, 0x300, v100
	v_ashrrev_i32_e32 v101, 31, v100
	v_lshl_add_u64 v[100:101], v[100:101], 2, v[2:3]
	global_load_dword v240, v[100:101], off
	v_or_b32_e32 v100, s10, v32
	v_mul_i32_i24_e32 v100, 0x300, v100
	v_ashrrev_i32_e32 v101, 31, v100
	v_lshl_add_u64 v[100:101], v[100:101], 2, v[2:3]
	global_load_dword v240, v[100:101], off
	v_or_b32_e32 v100, s10, v33
	v_mul_i32_i24_e32 v100, 0x300, v100
	v_ashrrev_i32_e32 v101, 31, v100
	v_lshl_add_u64 v[100:101], v[100:101], 2, v[2:3]
	global_load_dword v240, v[100:101], off
	v_or_b32_e32 v100, s10, v34
	v_mul_i32_i24_e32 v100, 0x300, v100
	v_ashrrev_i32_e32 v101, 31, v100
	v_lshl_add_u64 v[100:101], v[100:101], 2, v[2:3]
	global_load_dword v240, v[100:101], off
	v_or_b32_e32 v100, s10, v35
	v_mul_i32_i24_e32 v100, 0x300, v100
	v_ashrrev_i32_e32 v101, 31, v100
	v_lshl_add_u64 v[100:101], v[100:101], 2, v[2:3]
	global_load_dword v240, v[100:101], off
	v_or_b32_e32 v100, s10, v36
	v_mul_i32_i24_e32 v100, 0x300, v100
	v_ashrrev_i32_e32 v101, 31, v100
	v_lshl_add_u64 v[100:101], v[100:101], 2, v[2:3]
	global_load_dword v240, v[100:101], off
	v_or_b32_e32 v100, s10, v37
	v_mul_i32_i24_e32 v100, 0x300, v100
	v_ashrrev_i32_e32 v101, 31, v100
	v_lshl_add_u64 v[100:101], v[100:101], 2, v[2:3]
	global_load_dword v240, v[100:101], off
	v_mul_i32_i24_e32 v46, 0x300, v4
	v_ashrrev_i32_e32 v47, 31, v46
	v_lshl_add_u64 v[46:47], v[46:47], 2, v[2:3]
	global_load_dword v45, v[46:47], off

; __device__ __forceinline__ void transpose_item(const float* W, int K, int Nsrc, bf16_t* WT, int dst_n0, int src_n0, int nvalid, const float* kgain, int k0, LAS float* scr, int lane) {
;     ...
; #pragma unroll 32
;     for (int i = 0; i < 32; ++i) { const int kk = 2 * i + (lane >> 5);
;         float v = (srcn < nvalid) ? W[(size_t)(k0 + kk) * Nsrc + srcn] : 0.f;
;         if (kgain) v *= kgain[k0 + kk];
;         scr[kk * 33 + (lane & 31)] = v; }
; __device__ __forceinline__ void convert_group(const Frame& F, const float* W, int nl, int K, int Nsrc, int Ndst, bf16_t* WT, int kind, const float* kgain, int gain_stride) {
;     ...
;     for (int it = F.gw; it < total; it += F.NGW) {
;         const int l = it / per, r = it % per, kb = r / nblk, nb = r % nblk, dn0 = nb * 32;
;         int sn0 = dn0;
;         if (kind == 1) { const int j = dn0 >> 8, i0 = dn0 & 255; sn0 = (i0 < 128) ? (128 * j + i0) : (D_FF + 128 * j + i0 - 128); }
;         transpose_item(W + (size_t)l * K * Nsrc, K, Nsrc, WT + (size_t)l * Ndst * K, dn0, sn0, Nsrc, kgain ? kgain + l * gain_stride : nullptr, kb * 64, scr, lane_l);
.LBB0_807:
	s_ashr_i32 s6, s24, 31
	s_lshr_b32 s6, s6, 25
	s_add_i32 s6, s24, s6
	s_ashr_i32 s16, s6, 7
	s_and_b32 s6, s6, 0xff80
	s_sub_i32 s6, s24, s6
	s_bfe_i32 s7, s6, 0x80000
	s_bfe_u32 s7, s7, 0x5000a
	s_add_i32 s7, s6, s7
	s_bfe_i32 s8, s7, 0x80000
	s_and_b32 s7, s7, 0xe0
	s_sub_i32 s6, s6, s7
	s_sext_i32_i8 s6, s6
	s_ashr_i32 s17, s16, 31
	s_lshl_b32 s25, s6, 5
	s_lshl_b64 s[6:7], s[16:17], 20
	s_sext_i32_i16 s10, s8
	s_add_u32 s8, s14, s6
	s_addc_u32 s9, s15, s7
	s_lshl_b32 s6, s10, 1
	v_or_b32_e32 v2, s25, v7
	s_and_b32 s10, s6, 0xffffffc0
	s_movk_i32 s6, 0x400
	v_ashrrev_i32_e32 v3, 31, v2
	v_cmp_gt_i32_e64 s[6:7], s6, v2
	v_lshl_add_u64 v[2:3], v[2:3], 2, s[8:9]
	v_mov_b32_e32 v45, 0
	v_or_b32_e32 v4, s10, v0
	s_and_saveexec_b64 s[8:9], s[6:7]
	s_cbranch_execz .LBB0_809
	v_or_b32_e32 v100, s10, v8
	v_ashrrev_i32_e32 v101, 31, v100
	v_lshlrev_b64 v[100:101], 12, v[100:101]
	v_lshl_add_u64 v[100:101], v[2:3], 0, v[100:101]
	global_load_dword v240, v[100:101], off
	v_or_b32_e32 v100, s10, v9
	v_ashrrev_i32_e32 v101, 31, v100
	v_lshlrev_b64 v[100:101], 12, v[100:101]
	v_lshl_add_u64 v[100:101], v[2:3], 0, v[100:101]
	global_load_dword v240, v[100:101], off
	v_or_b32_e32 v100, s10, v10
	v_ashrrev_i32_e32 v101, 31, v100
	v_lshlrev_b64 v[100:101], 12, v[100:101]
	v_lshl_add_u64 v[100:101], v[2:3], 0, v[100:101]
	global_load_dword v240, v[100:101], off
	v_or_b32_e32 v100, s10, v11
	v_ashrrev_i32_e32 v101, 31, v100
	v_lshlrev_b64 v[100:101], 12, v[100:101]
	v_lshl_add_u64 v[100:101], v[2:3], 0, v[100:101]
	global_load_dword v240, v[100:101], off
	v_or_b32_e32 v100, s10, v12
	v_ashrrev_i32_e32 v101, 31, v100
	v_lshlrev_b64 v[100:101], 12, v[100:101]
	v_lshl_add_u64 v[100:101], v[2:3], 0, v[100:101]
	global_load_dword v240, v[100:101], off
	v_or_b32_e32 v100, s10, v13
	v_ashrrev_i32_e32 v101, 31, v100
	v_lshlrev_b64 v[100:101], 12, v[100:101]
	v_lshl_add_u64 v[100:101], v[2:3], 0, v[100:101]
	global_load_dword v240, v[100:101], off
	v_or_b32_e32 v100, s10, v14
	v_ashrrev_i32_e32 v101, 31, v100
	v_lshlrev_b64 v[100:101], 12, v[100:101]
	v_lshl_add_u64 v[100:101], v[2:3], 0, v[100:101]
	global_load_dword v240, v[100:101], off
	v_or_b32_e32 v100, s10, v15
	v_ashrrev_i32_e32 v101, 31, v100
	v_lshlrev_b64 v[100:101], 12, v[100:101]
	v_lshl_add_u64 v[100:101], v[2:3], 0, v[100:101]
	global_load_dword v240, v[100:101], off
	v_or_b32_e32 v100, s10, v16
	v_ashrrev_i32_e32 v101, 31, v100
	v_lshlrev_b64 v[100:101], 12, v[100:101]
	v_lshl_add_u64 v[100:101], v[2:3], 0, v[100:101]
	global_load_dword v240, v[100:101], off
	v_or_b32_e32 v100, s10, v17
	v_ashrrev_i32_e32 v101, 31, v100
	v_lshlrev_b64 v[100:101], 12, v[100:101]
	v_lshl_add_u64 v[100:101], v[2:3], 0, v[100:101]
	global_load_dword v240, v[100:101], off
	v_or_b32_e32 v100, s10, v18
	v_ashrrev_i32_e32 v101, 31, v100
	v_lshlrev_b64 v[100:101], 12, v[100:101]
	v_lshl_add_u64 v[100:101], v[2:3], 0, v[100:101]
	global_load_dword v240, v[100:101], off
	v_or_b32_e32 v100, s10, v19
	v_ashrrev_i32_e32 v101, 31, v100
	v_lshlrev_b64 v[100:101], 12, v[100:101]
	v_lshl_add_u64 v[100:101], v[2:3], 0, v[100:101]
	global_load_dword v240, v[100:101], off
	v_or_b32_e32 v100, s10, v20
	v_ashrrev_i32_e32 v101, 31, v100
	v_lshlrev_b64 v[100:101], 12, v[100:101]
	v_lshl_add_u64 v[100:101], v[2:3], 0, v[100:101]
	global_load_dword v240, v[100:101], off
	v_or_b32_e32 v100, s10, v21
	v_ashrrev_i32_e32 v101, 31, v100
	v_lshlrev_b64 v[100:101], 12, v[100:101]
	v_lshl_add_u64 v[100:101], v[2:3], 0, v[100:101]
	global_load_dword v240, v[100:101], off
	v_or_b32_e32 v100, s10, v22
	v_ashrrev_i32_e32 v101, 31, v100
	v_lshlrev_b64 v[100:101], 12, v[100:101]
	v_lshl_add_u64 v[100:101], v[2:3], 0, v[100:101]
	global_load_dword v240, v[100:101], off
	v_or_b32_e32 v100, s10, v23
	v_ashrrev_i32_e32 v101, 31, v100
	v_lshlrev_b64 v[100:101], 12, v[100:101]
	v_lshl_add_u64 v[100:101], v[2:3], 0, v[100:101]
	global_load_dword v240, v[100:101], off
	v_or_b32_e32 v100, s10, v24
	v_ashrrev_i32_e32 v101, 31, v100
	v_lshlrev_b64 v[100:101], 12, v[100:101]
	v_lshl_add_u64 v[100:101], v[2:3], 0, v[100:101]
	global_load_dword v240, v[100:101], off
	v_or_b32_e32 v100, s10, v25
	v_ashrrev_i32_e32 v101, 31, v100
	v_lshlrev_b64 v[100:101], 12, v[100:101]
	v_lshl_add_u64 v[100:101], v[2:3], 0, v[100:101]
	global_load_dword v240, v[100:101], off
	v_or_b32_e32 v100, s10, v26
	v_ashrrev_i32_e32 v101, 31, v100
	v_lshlrev_b64 v[100:101], 12, v[100:101]
	v_lshl_add_u64 v[100:101], v[2:3], 0, v[100:101]
	global_load_dword v240, v[100:101], off
	v_or_b32_e32 v100, s10, v27
	v_ashrrev_i32_e32 v101, 31, v100
	v_lshlrev_b64 v[100:101], 12, v[100:101]
	v_lshl_add_u64 v[100:101], v[2:3], 0, v[100:101]
	global_load_dword v240, v[100:101], off
	v_or_b32_e32 v100, s10, v28
	v_ashrrev_i32_e32 v101, 31, v100
	v_lshlrev_b64 v[100:101], 12, v[100:101]
	v_lshl_add_u64 v[100:101], v[2:3], 0, v[100:101]
	global_load_dword v240, v[100:101], off
	v_or_b32_e32 v100, s10, v29
	v_ashrrev_i32_e32 v101, 31, v100
	v_lshlrev_b64 v[100:101], 12, v[100:101]
	v_lshl_add_u64 v[100:101], v[2:3], 0, v[100:101]
	global_load_dword v240, v[100:101], off
	v_or_b32_e32 v100, s10, v30
	v_ashrrev_i32_e32 v101, 31, v100
	v_lshlrev_b64 v[100:101], 12, v[100:101]
	v_lshl_add_u64 v[100:101], v[2:3], 0, v[100:101]
	global_load_dword v240, v[100:101], off
	v_or_b32_e32 v100, s10, v31
	v_ashrrev_i32_e32 v101, 31, v100
	v_lshlrev_b64 v[100:101], 12, v[100:101]
	v_lshl_add_u64 v[100:101], v[2:3], 0, v[100:101]
	global_load_dword v240, v[100:101], off
	v_or_b32_e32 v100, s10, v32
	v_ashrrev_i32_e32 v101, 31, v100
	v_lshlrev_b64 v[100:101], 12, v[100:101]
	v_lshl_add_u64 v[100:101], v[2:3], 0, v[100:101]
	global_load_dword v240, v[100:101], off
	v_or_b32_e32 v100, s10, v33
	v_ashrrev_i32_e32 v101, 31, v100
	v_lshlrev_b64 v[100:101], 12, v[100:101]
	v_lshl_add_u64 v[100:101], v[2:3], 0, v[100:101]
	global_load_dword v240, v[100:101], off
	v_or_b32_e32 v100, s10, v34
	v_ashrrev_i32_e32 v101, 31, v100
	v_lshlrev_b64 v[100:101], 12, v[100:101]
	v_lshl_add_u64 v[100:101], v[2:3], 0, v[100:101]
	global_load_dword v240, v[100:101], off
	v_or_b32_e32 v100, s10, v35
	v_ashrrev_i32_e32 v101, 31, v100
	v_lshlrev_b64 v[100:101], 12, v[100:101]
	v_lshl_add_u64 v[100:101], v[2:3], 0, v[100:101]
	global_load_dword v240, v[100:101], off
	v_or_b32_e32 v100, s10, v36
	v_ashrrev_i32_e32 v101, 31, v100
	v_lshlrev_b64 v[100:101], 12, v[100:101]
	v_lshl_add_u64 v[100:101], v[2:3], 0, v[100:101]
	global_load_dword v240, v[100:101], off
	v_or_b32_e32 v100, s10, v37
	v_ashrrev_i32_e32 v101, 31, v100
	v_lshlrev_b64 v[100:101], 12, v[100:101]
	v_lshl_add_u64 v[100:101], v[2:3], 0, v[100:101]
	global_load_dword v240, v[100:101], off
	v_ashrrev_i32_e32 v5, 31, v4
	v_lshlrev_b64 v[46:47], 12, v[4:5]
	v_lshl_add_u64 v[46:47], v[2:3], 0, v[46:47]
	global_load_dword v45, v[46:47], off

; __device__ __forceinline__ void transpose_item(const float* W, int K, int Nsrc, bf16_t* WT, int dst_n0, int src_n0, int nvalid, const float* kgain, int k0, LAS float* scr, int lane) {
;     ...
; #pragma unroll 32
;     for (int i = 0; i < 32; ++i) { const int kk = 2 * i + (lane >> 5);
;         float v = (srcn < nvalid) ? W[(size_t)(k0 + kk) * Nsrc + srcn] : 0.f;
;         if (kgain) v *= kgain[k0 + kk];
;         scr[kk * 33 + (lane & 31)] = v; }
; __device__ __forceinline__ void convert_group(const Frame& F, const float* W, int nl, int K, int Nsrc, int Ndst, bf16_t* WT, int kind, const float* kgain, int gain_stride) {
;     ...
;     for (int it = F.gw; it < total; it += F.NGW) {
;         const int l = it / per, r = it % per, kb = r / nblk, nb = r % nblk, dn0 = nb * 32;
;         int sn0 = dn0;
;         if (kind == 1) { const int j = dn0 >> 8, i0 = dn0 & 255; sn0 = (i0 < 128) ? (128 * j + i0) : (D_FF + 128 * j + i0 - 128); }
;         transpose_item(W + (size_t)l * K * Nsrc, K, Nsrc, WT + (size_t)l * Ndst * K, dn0, sn0, Nsrc, kgain ? kgain + l * gain_stride : nullptr, kb * 64, scr, lane_l);
.LBB0_941:
	s_ashr_i32 s8, s18, 31
	s_lshr_b32 s8, s8, 23
	s_add_i32 s9, s18, s8
	s_ashr_i32 s8, s9, 9
	s_and_b32 s9, s9, 0xfe00
	s_sub_i32 s9, s18, s9
	s_sext_i32_i16 s10, s9
	s_bfe_u32 s10, s10, 0x5001a
	s_add_i32 s20, s9, s10
	s_and_b32 s10, s20, 0xffe0
	s_sub_i32 s9, s9, s10
	s_sext_i32_i16 s9, s9
	s_lshl_b32 s19, s9, 5
	s_ashr_i32 s9, s8, 31
	s_lshl_b64 s[10:11], s[8:9], 22
	s_add_u32 s14, s6, s10
	v_or_b32_e32 v0, s19, v2
	s_addc_u32 s15, s7, s11
	v_cmp_lt_i32_e32 vcc, s48, v0
	s_and_saveexec_b64 s[10:11], vcc
	s_xor_b64 s[10:11], exec, s[10:11]
	ds_write2_b32 v43, v165, v165 offset1:66
	s_or_saveexec_b64 s[12:13], s[10:11]
	s_sext_i32_i16 s10, s20
	s_lshl_b32 s10, s10, 1
	v_ashrrev_i32_e32 v1, 31, v0
	s_andn2_b32 s10, s10, 63
	v_lshl_add_u64 v[0:1], v[0:1], 2, s[14:15]
	v_mov_b32_e32 v46, 0
	v_mov_b32_e32 v47, 0
	s_xor_b64 exec, exec, s[12:13]
	s_cbranch_execz .LBB0_945
	v_or_b32_e32 v46, s10, v8
	v_or_b32_e32 v48, s10, v9
	v_ashrrev_i32_e32 v47, 31, v46
	v_ashrrev_i32_e32 v49, 31, v48
	v_or_b32_e32 v50, s10, v10
	v_or_b32_e32 v52, s10, v11
	v_lshlrev_b64 v[46:47], 12, v[46:47]
	v_lshlrev_b64 v[48:49], 12, v[48:49]
	v_ashrrev_i32_e32 v51, 31, v50
	v_ashrrev_i32_e32 v53, 31, v52
	v_lshl_add_u64 v[46:47], v[0:1], 0, v[46:47]
	v_lshl_add_u64 v[48:49], v[0:1], 0, v[48:49]
	v_lshlrev_b64 v[50:51], 12, v[50:51]
	v_lshlrev_b64 v[52:53], 12, v[52:53]
	v_lshl_add_u64 v[50:51], v[0:1], 0, v[50:51]
	v_lshl_add_u64 v[52:53], v[0:1], 0, v[52:53]
	global_load_dword v240, v[46:47], off
	global_load_dword v240, v[48:49], off
	global_load_dword v240, v[50:51], off
	global_load_dword v240, v[52:53], off
	v_or_b32_e32 v46, s10, v12
	v_or_b32_e32 v48, s10, v13
	v_ashrrev_i32_e32 v47, 31, v46
	v_ashrrev_i32_e32 v49, 31, v48
	v_or_b32_e32 v50, s10, v14
	v_or_b32_e32 v52, s10, v15
	v_lshlrev_b64 v[46:47], 12, v[46:47]
	v_lshlrev_b64 v[48:49], 12, v[48:49]
	v_ashrrev_i32_e32 v51, 31, v50
	v_ashrrev_i32_e32 v53, 31, v52
	v_lshl_add_u64 v[46:47], v[0:1], 0, v[46:47]
	v_lshl_add_u64 v[48:49], v[0:1], 0, v[48:49]
	v_lshlrev_b64 v[50:51], 12, v[50:51]
	v_lshlrev_b64 v[52:53], 12, v[52:53]
	v_lshl_add_u64 v[50:51], v[0:1], 0, v[50:51]
	v_lshl_add_u64 v[52:53], v[0:1], 0, v[52:53]
	global_load_dword v240, v[46:47], off
	global_load_dword v240, v[48:49], off
	global_load_dword v240, v[50:51], off
	global_load_dword v240, v[52:53], off
	v_or_b32_e32 v48, s10, v16
	v_or_b32_e32 v50, s10, v17
	v_ashrrev_i32_e32 v49, 31, v48
	v_ashrrev_i32_e32 v51, 31, v50
	v_or_b32_e32 v52, s10, v18
	v_or_b32_e32 v54, s10, v19
	v_lshlrev_b64 v[48:49], 12, v[48:49]
	v_lshlrev_b64 v[50:51], 12, v[50:51]
	v_ashrrev_i32_e32 v53, 31, v52
	v_ashrrev_i32_e32 v55, 31, v54
	v_lshl_add_u64 v[48:49], v[0:1], 0, v[48:49]
	v_lshl_add_u64 v[50:51], v[0:1], 0, v[50:51]
	v_lshlrev_b64 v[52:53], 12, v[52:53]
	v_lshlrev_b64 v[54:55], 12, v[54:55]
	v_lshl_add_u64 v[52:53], v[0:1], 0, v[52:53]
	v_lshl_add_u64 v[54:55], v[0:1], 0, v[54:55]
	global_load_dword v240, v[48:49], off
	global_load_dword v240, v[50:51], off
	global_load_dword v240, v[52:53], off
	global_load_dword v240, v[54:55], off
	v_or_b32_e32 v48, s10, v20
	v_or_b32_e32 v50, s10, v21
	v_ashrrev_i32_e32 v49, 31, v48
	v_ashrrev_i32_e32 v51, 31, v50
	v_or_b32_e32 v52, s10, v22
	v_or_b32_e32 v54, s10, v23
	v_lshlrev_b64 v[48:49], 12, v[48:49]
	v_lshlrev_b64 v[50:51], 12, v[50:51]
	v_ashrrev_i32_e32 v53, 31, v52
	v_ashrrev_i32_e32 v55, 31, v54
	v_lshl_add_u64 v[48:49], v[0:1], 0, v[48:49]
	v_lshl_add_u64 v[50:51], v[0:1], 0, v[50:51]
	v_lshlrev_b64 v[52:53], 12, v[52:53]
	v_lshlrev_b64 v[54:55], 12, v[54:55]
	v_lshl_add_u64 v[52:53], v[0:1], 0, v[52:53]
	v_lshl_add_u64 v[54:55], v[0:1], 0, v[54:55]
	global_load_dword v240, v[48:49], off
	global_load_dword v240, v[50:51], off
	global_load_dword v240, v[52:53], off
	global_load_dword v240, v[54:55], off
	v_or_b32_e32 v48, s10, v24
	v_or_b32_e32 v50, s10, v25
	v_ashrrev_i32_e32 v49, 31, v48
	v_ashrrev_i32_e32 v51, 31, v50
	v_or_b32_e32 v52, s10, v26
	v_or_b32_e32 v54, s10, v27
	v_lshlrev_b64 v[48:49], 12, v[48:49]
	v_lshlrev_b64 v[50:51], 12, v[50:51]
	v_ashrrev_i32_e32 v53, 31, v52
	v_ashrrev_i32_e32 v55, 31, v54
	v_lshl_add_u64 v[48:49], v[0:1], 0, v[48:49]
	v_lshl_add_u64 v[50:51], v[0:1], 0, v[50:51]
	v_lshlrev_b64 v[52:53], 12, v[52:53]
	v_lshlrev_b64 v[54:55], 12, v[54:55]
	v_lshl_add_u64 v[52:53], v[0:1], 0, v[52:53]
	v_lshl_add_u64 v[54:55], v[0:1], 0, v[54:55]
	global_load_dword v240, v[48:49], off
	global_load_dword v240, v[50:51], off
	global_load_dword v240, v[52:53], off
	global_load_dword v240, v[54:55], off
	v_or_b32_e32 v48, s10, v28
	v_or_b32_e32 v50, s10, v29
	v_ashrrev_i32_e32 v49, 31, v48
	v_ashrrev_i32_e32 v51, 31, v50
	v_or_b32_e32 v52, s10, v30
	v_or_b32_e32 v54, s10, v31
	v_lshlrev_b64 v[48:49], 12, v[48:49]
	v_lshlrev_b64 v[50:51], 12, v[50:51]
	v_ashrrev_i32_e32 v53, 31, v52
	v_ashrrev_i32_e32 v55, 31, v54
	v_lshl_add_u64 v[48:49], v[0:1], 0, v[48:49]
	v_lshl_add_u64 v[50:51], v[0:1], 0, v[50:51]
	v_lshlrev_b64 v[52:53], 12, v[52:53]
	v_lshlrev_b64 v[54:55], 12, v[54:55]
	v_lshl_add_u64 v[52:53], v[0:1], 0, v[52:53]
	v_lshl_add_u64 v[54:55], v[0:1], 0, v[54:55]
	global_load_dword v240, v[48:49], off
	global_load_dword v240, v[50:51], off
	global_load_dword v240, v[52:53], off
	global_load_dword v240, v[54:55], off
	v_or_b32_e32 v48, s10, v32
	v_or_b32_e32 v50, s10, v33
	v_ashrrev_i32_e32 v49, 31, v48
	v_ashrrev_i32_e32 v51, 31, v50
	v_or_b32_e32 v52, s10, v34
	v_or_b32_e32 v54, s10, v35
	v_lshlrev_b64 v[48:49], 12, v[48:49]
	v_lshlrev_b64 v[50:51], 12, v[50:51]
	v_ashrrev_i32_e32 v53, 31, v52
	v_ashrrev_i32_e32 v55, 31, v54
	v_lshl_add_u64 v[48:49], v[0:1], 0, v[48:49]
	v_lshl_add_u64 v[50:51], v[0:1], 0, v[50:51]
	v_lshlrev_b64 v[52:53], 12, v[52:53]
	v_lshlrev_b64 v[54:55], 12, v[54:55]
	v_lshl_add_u64 v[52:53], v[0:1], 0, v[52:53]
	v_lshl_add_u64 v[54:55], v[0:1], 0, v[54:55]
	global_load_dword v240, v[48:49], off
	global_load_dword v240, v[50:51], off
	global_load_dword v240, v[52:53], off
	global_load_dword v240, v[54:55], off
	v_or_b32_e32 v46, s10, v3
	v_or_b32_e32 v48, s10, v4
	v_ashrrev_i32_e32 v47, 31, v46
	v_ashrrev_i32_e32 v49, 31, v48
	v_or_b32_e32 v50, s10, v5
	v_or_b32_e32 v52, s10, v7
	v_lshlrev_b64 v[46:47], 12, v[46:47]
	v_lshlrev_b64 v[48:49], 12, v[48:49]
	v_ashrrev_i32_e32 v51, 31, v50
	v_ashrrev_i32_e32 v53, 31, v52
	v_lshl_add_u64 v[46:47], v[0:1], 0, v[46:47]
	v_lshl_add_u64 v[48:49], v[0:1], 0, v[48:49]
	v_lshlrev_b64 v[50:51], 12, v[50:51]
	v_lshlrev_b64 v[52:53], 12, v[52:53]
	v_lshl_add_u64 v[50:51], v[0:1], 0, v[50:51]
	v_lshl_add_u64 v[52:53], v[0:1], 0, v[52:53]
	global_load_dword v54, v[46:47], off
	s_nop 0
	global_load_dword v48, v[48:49], off
	s_nop 0
	global_load_dword v46, v[50:51], off
	global_load_dword v47, v[52:53], off
	s_waitcnt vmcnt(2)
	ds_write2_b32 v43, v54, v48 offset1:66

; __device__ __forceinline__ void transpose_item(const float* W, int K, int Nsrc, bf16_t* WT, int dst_n0, int src_n0, int nvalid, const float* kgain, int k0, LAS float* scr, int lane) {
;     ...
; #pragma unroll 32
;     for (int i = 0; i < 32; ++i) { const int kk = 2 * i + (lane >> 5);
;         float v = (srcn < nvalid) ? W[(size_t)(k0 + kk) * Nsrc + srcn] : 0.f;
;         if (kgain) v *= kgain[k0 + kk];
;         scr[kk * 33 + (lane & 31)] = v; }
; __device__ __forceinline__ void convert_group(const Frame& F, const float* W, int nl, int K, int Nsrc, int Ndst, bf16_t* WT, int kind, const float* kgain, int gain_stride) {
;     ...
;     for (int it = F.gw; it < total; it += F.NGW) {
;         const int l = it / per, r = it % per, kb = r / nblk, nb = r % nblk, dn0 = nb * 32;
;         int sn0 = dn0;
;         if (kind == 1) { const int j = dn0 >> 8, i0 = dn0 & 255; sn0 = (i0 < 128) ? (128 * j + i0) : (D_FF + 128 * j + i0 - 128); }
;         transpose_item(W + (size_t)l * K * Nsrc, K, Nsrc, WT + (size_t)l * Ndst * K, dn0, sn0, Nsrc, kgain ? kgain + l * gain_stride : nullptr, kb * 64, scr, lane_l);
.LBB0_977:
	s_mul_hi_i32 s8, s18, 0x2aaaaaab
	s_lshr_b32 s9, s8, 31
	s_ashr_i32 s8, s8, 8
	s_add_i32 s8, s8, s9
	s_mul_i32 s9, s8, 0xfffffa00
	s_add_i32 s9, s18, s9
	s_mul_i32 s10, s9, 0x2aab
	s_lshr_b32 s11, s10, 31
	s_ashr_i32 s20, s10, 20
	s_add_i32 s20, s20, s11
	s_mul_i32 s10, s20, 0x60
	s_sub_i32 s9, s9, s10
	s_sext_i32_i16 s9, s9
	s_mul_hi_i32 s11, s8, 0x300000
	s_mul_i32 s10, s8, 0x300000
	s_lshl_b32 s19, s9, 5
	s_lshl_b64 s[8:9], s[10:11], 2
	s_add_u32 s14, s6, s8
	v_or_b32_e32 v0, s19, v2
	s_movk_i32 s8, 0xbff
	s_addc_u32 s15, s7, s9
	v_cmp_lt_i32_e32 vcc, s8, v0
	s_and_saveexec_b64 s[8:9], vcc
	s_xor_b64 s[8:9], exec, s[8:9]
	ds_write2_b32 v43, v165, v165 offset1:66
	s_or_saveexec_b64 s[12:13], s[8:9]
	v_ashrrev_i32_e32 v1, 31, v0
	s_lshl_b32 s8, s20, 6
	v_lshl_add_u64 v[0:1], v[0:1], 2, s[14:15]
	v_mov_b32_e32 v46, 0
	v_mov_b32_e32 v47, 0
	s_xor_b64 exec, exec, s[12:13]
	s_cbranch_execz .LBB0_981
	v_or_b32_e32 v46, s8, v8
	v_or_b32_e32 v48, s8, v9
	v_mul_i32_i24_e32 v46, 0xc00, v46
	v_mul_i32_i24_e32 v48, 0xc00, v48
	v_or_b32_e32 v50, s8, v10
	v_or_b32_e32 v52, s8, v11
	v_ashrrev_i32_e32 v47, 31, v46
	v_ashrrev_i32_e32 v49, 31, v48
	v_mul_i32_i24_e32 v50, 0xc00, v50
	v_mul_i32_i24_e32 v52, 0xc00, v52
	v_lshl_add_u64 v[46:47], v[46:47], 2, v[0:1]
	v_lshl_add_u64 v[48:49], v[48:49], 2, v[0:1]
	v_ashrrev_i32_e32 v51, 31, v50
	v_ashrrev_i32_e32 v53, 31, v52
	v_lshl_add_u64 v[50:51], v[50:51], 2, v[0:1]
	v_lshl_add_u64 v[52:53], v[52:53], 2, v[0:1]
	global_load_dword v240, v[46:47], off
	global_load_dword v240, v[48:49], off
	global_load_dword v240, v[50:51], off
	global_load_dword v240, v[52:53], off
	v_or_b32_e32 v46, s8, v12
	v_or_b32_e32 v48, s8, v13
	v_mul_i32_i24_e32 v46, 0xc00, v46
	v_mul_i32_i24_e32 v48, 0xc00, v48
	v_or_b32_e32 v50, s8, v14
	v_or_b32_e32 v52, s8, v15
	v_ashrrev_i32_e32 v47, 31, v46
	v_ashrrev_i32_e32 v49, 31, v48
	v_mul_i32_i24_e32 v50, 0xc00, v50
	v_mul_i32_i24_e32 v52, 0xc00, v52
	v_lshl_add_u64 v[46:47], v[46:47], 2, v[0:1]
	v_lshl_add_u64 v[48:49], v[48:49], 2, v[0:1]
	v_ashrrev_i32_e32 v51, 31, v50
	v_ashrrev_i32_e32 v53, 31, v52
	v_lshl_add_u64 v[50:51], v[50:51], 2, v[0:1]
	v_lshl_add_u64 v[52:53], v[52:53], 2, v[0:1]
	global_load_dword v240, v[46:47], off
	global_load_dword v240, v[48:49], off
	global_load_dword v240, v[50:51], off
	global_load_dword v240, v[52:53], off
	v_or_b32_e32 v47, s8, v16
	v_mul_i32_i24_e32 v48, 0xc00, v47
	v_or_b32_e32 v47, s8, v17
	v_mul_i32_i24_e32 v50, 0xc00, v47
	v_or_b32_e32 v47, s8, v18
	v_mul_i32_i24_e32 v52, 0xc00, v47
	v_or_b32_e32 v47, s8, v19
	v_ashrrev_i32_e32 v49, 31, v48
	v_ashrrev_i32_e32 v51, 31, v50
	v_mul_i32_i24_e32 v54, 0xc00, v47
	v_lshl_add_u64 v[48:49], v[48:49], 2, v[0:1]
	v_lshl_add_u64 v[50:51], v[50:51], 2, v[0:1]
	v_ashrrev_i32_e32 v53, 31, v52
	v_ashrrev_i32_e32 v55, 31, v54
	v_lshl_add_u64 v[52:53], v[52:53], 2, v[0:1]
	v_lshl_add_u64 v[54:55], v[54:55], 2, v[0:1]
	global_load_dword v240, v[48:49], off
	global_load_dword v240, v[50:51], off
	global_load_dword v240, v[52:53], off
	global_load_dword v240, v[54:55], off
	v_or_b32_e32 v47, s8, v20
	v_mul_i32_i24_e32 v48, 0xc00, v47
	v_or_b32_e32 v47, s8, v21
	v_mul_i32_i24_e32 v50, 0xc00, v47
	v_or_b32_e32 v47, s8, v22
	v_mul_i32_i24_e32 v52, 0xc00, v47
	v_or_b32_e32 v47, s8, v23
	v_ashrrev_i32_e32 v49, 31, v48
	v_ashrrev_i32_e32 v51, 31, v50
	v_mul_i32_i24_e32 v54, 0xc00, v47
	v_lshl_add_u64 v[48:49], v[48:49], 2, v[0:1]
	v_lshl_add_u64 v[50:51], v[50:51], 2, v[0:1]
	v_ashrrev_i32_e32 v53, 31, v52
	v_ashrrev_i32_e32 v55, 31, v54
	v_lshl_add_u64 v[52:53], v[52:53], 2, v[0:1]
	v_lshl_add_u64 v[54:55], v[54:55], 2, v[0:1]
	global_load_dword v240, v[48:49], off
	global_load_dword v240, v[50:51], off
	global_load_dword v240, v[52:53], off
	global_load_dword v240, v[54:55], off
	v_or_b32_e32 v47, s8, v24
	v_mul_i32_i24_e32 v48, 0xc00, v47
	v_or_b32_e32 v47, s8, v25
	v_mul_i32_i24_e32 v50, 0xc00, v47
	v_or_b32_e32 v47, s8, v26
	v_mul_i32_i24_e32 v52, 0xc00, v47
	v_or_b32_e32 v47, s8, v27
	v_ashrrev_i32_e32 v49, 31, v48
	v_ashrrev_i32_e32 v51, 31, v50
	v_mul_i32_i24_e32 v54, 0xc00, v47
	v_lshl_add_u64 v[48:49], v[48:49], 2, v[0:1]
	v_lshl_add_u64 v[50:51], v[50:51], 2, v[0:1]
	v_ashrrev_i32_e32 v53, 31, v52
	v_ashrrev_i32_e32 v55, 31, v54
	v_lshl_add_u64 v[52:53], v[52:53], 2, v[0:1]
	v_lshl_add_u64 v[54:55], v[54:55], 2, v[0:1]
	global_load_dword v240, v[48:49], off
	global_load_dword v240, v[50:51], off
	global_load_dword v240, v[52:53], off
	global_load_dword v240, v[54:55], off
	v_or_b32_e32 v47, s8, v28
	v_mul_i32_i24_e32 v48, 0xc00, v47
	v_or_b32_e32 v47, s8, v29
	v_mul_i32_i24_e32 v50, 0xc00, v47
	v_or_b32_e32 v47, s8, v30
	v_mul_i32_i24_e32 v52, 0xc00, v47
	v_or_b32_e32 v47, s8, v31
	v_ashrrev_i32_e32 v49, 31, v48
	v_ashrrev_i32_e32 v51, 31, v50
	v_mul_i32_i24_e32 v54, 0xc00, v47
	v_lshl_add_u64 v[48:49], v[48:49], 2, v[0:1]
	v_lshl_add_u64 v[50:51], v[50:51], 2, v[0:1]
	v_ashrrev_i32_e32 v53, 31, v52
	v_ashrrev_i32_e32 v55, 31, v54
	v_lshl_add_u64 v[52:53], v[52:53], 2, v[0:1]
	v_lshl_add_u64 v[54:55], v[54:55], 2, v[0:1]
	global_load_dword v240, v[48:49], off
	global_load_dword v240, v[50:51], off
	global_load_dword v240, v[52:53], off
	global_load_dword v240, v[54:55], off
	v_or_b32_e32 v47, s8, v32
	v_mul_i32_i24_e32 v48, 0xc00, v47
	v_or_b32_e32 v47, s8, v33
	v_mul_i32_i24_e32 v50, 0xc00, v47
	v_or_b32_e32 v47, s8, v34
	v_mul_i32_i24_e32 v52, 0xc00, v47
	v_or_b32_e32 v47, s8, v35
	v_ashrrev_i32_e32 v49, 31, v48
	v_ashrrev_i32_e32 v51, 31, v50
	v_mul_i32_i24_e32 v54, 0xc00, v47
	v_lshl_add_u64 v[48:49], v[48:49], 2, v[0:1]
	v_lshl_add_u64 v[50:51], v[50:51], 2, v[0:1]
	v_ashrrev_i32_e32 v53, 31, v52
	v_ashrrev_i32_e32 v55, 31, v54
	v_lshl_add_u64 v[52:53], v[52:53], 2, v[0:1]
	v_lshl_add_u64 v[54:55], v[54:55], 2, v[0:1]
	global_load_dword v240, v[48:49], off
	global_load_dword v240, v[50:51], off
	global_load_dword v240, v[52:53], off
	global_load_dword v240, v[54:55], off
	v_or_b32_e32 v46, s8, v3
	v_or_b32_e32 v48, s8, v4
	v_mul_i32_i24_e32 v46, 0xc00, v46
	v_mul_i32_i24_e32 v48, 0xc00, v48
	v_or_b32_e32 v50, s8, v5
	v_or_b32_e32 v52, s8, v7
	v_ashrrev_i32_e32 v47, 31, v46
	v_ashrrev_i32_e32 v49, 31, v48
	v_mul_i32_i24_e32 v50, 0xc00, v50
	v_mul_i32_i24_e32 v52, 0xc00, v52
	v_lshl_add_u64 v[46:47], v[46:47], 2, v[0:1]
	v_lshl_add_u64 v[48:49], v[48:49], 2, v[0:1]
	v_ashrrev_i32_e32 v51, 31, v50
	v_ashrrev_i32_e32 v53, 31, v52
	v_lshl_add_u64 v[50:51], v[50:51], 2, v[0:1]
	v_lshl_add_u64 v[52:53], v[52:53], 2, v[0:1]
	global_load_dword v54, v[46:47], off
	s_nop 0
	global_load_dword v48, v[48:49], off
	s_nop 0
	global_load_dword v46, v[50:51], off
	global_load_dword v47, v[52:53], off
	s_waitcnt vmcnt(2)
	ds_write2_b32 v43, v54, v48 offset1:66

; __device__ __forceinline__ void transpose_item(const float* W, int K, int Nsrc, bf16_t* WT, int dst_n0, int src_n0, int nvalid, const float* kgain, int k0, LAS float* scr, int lane) {
;     ...
; #pragma unroll 32
;     for (int i = 0; i < 32; ++i) { const int kk = 2 * i + (lane >> 5);
;         float v = (srcn < nvalid) ? W[(size_t)(k0 + kk) * Nsrc + srcn] : 0.f;
;         if (kgain) v *= kgain[k0 + kk];
;         scr[kk * 33 + (lane & 31)] = v; }
; __device__ __forceinline__ void convert_group(const Frame& F, const float* W, int nl, int K, int Nsrc, int Ndst, bf16_t* WT, int kind, const float* kgain, int gain_stride) {
;     ...
;     for (int it = F.gw; it < total; it += F.NGW) {
;         const int l = it / per, r = it % per, kb = r / nblk, nb = r % nblk, dn0 = nb * 32;
;         int sn0 = dn0;
;         if (kind == 1) { const int j = dn0 >> 8, i0 = dn0 & 255; sn0 = (i0 < 128) ? (128 * j + i0) : (D_FF + 128 * j + i0 - 128); }
;         transpose_item(W + (size_t)l * K * Nsrc, K, Nsrc, WT + (size_t)l * Ndst * K, dn0, sn0, Nsrc, kgain ? kgain + l * gain_stride : nullptr, kb * 64, scr, lane_l);
.LBB0_1012:
	s_ashr_i32 s6, s16, 31
	s_lshr_b32 s6, s6, 23
	s_add_i32 s7, s16, s6
	s_ashr_i32 s6, s7, 9
	s_and_b32 s7, s7, 0xfe00
	s_sub_i32 s7, s16, s7
	s_sext_i32_i16 s8, s7
	s_bfe_u32 s8, s8, 0x5001a
	s_add_i32 s18, s7, s8
	s_and_b32 s8, s18, 0xffe0
	s_sub_i32 s7, s7, s8
	s_sext_i32_i16 s7, s7
	s_lshl_b32 s17, s7, 5
	s_ashr_i32 s7, s6, 31
	s_lshl_b64 s[8:9], s[6:7], 22
	s_add_u32 s12, s4, s8
	v_or_b32_e32 v0, s17, v2
	s_addc_u32 s13, s5, s9
	v_cmp_lt_i32_e32 vcc, s48, v0
	s_and_saveexec_b64 s[8:9], vcc
	s_xor_b64 s[8:9], exec, s[8:9]
	ds_write2_b32 v43, v165, v165 offset1:66
	s_or_saveexec_b64 s[10:11], s[8:9]
	s_sext_i32_i16 s8, s18
	s_lshl_b32 s8, s8, 1
	v_ashrrev_i32_e32 v1, 31, v0
	s_andn2_b32 s8, s8, 63
	v_lshl_add_u64 v[0:1], v[0:1], 2, s[12:13]
	v_mov_b32_e32 v46, 0
	v_mov_b32_e32 v47, 0
	s_xor_b64 exec, exec, s[10:11]
	s_cbranch_execz .LBB0_1016
	v_or_b32_e32 v46, s8, v8
	v_or_b32_e32 v48, s8, v9
	v_ashrrev_i32_e32 v47, 31, v46
	v_ashrrev_i32_e32 v49, 31, v48
	v_or_b32_e32 v50, s8, v10
	v_or_b32_e32 v52, s8, v11
	v_lshlrev_b64 v[46:47], 12, v[46:47]
	v_lshlrev_b64 v[48:49], 12, v[48:49]
	v_ashrrev_i32_e32 v51, 31, v50
	v_ashrrev_i32_e32 v53, 31, v52
	v_lshl_add_u64 v[46:47], v[0:1], 0, v[46:47]
	v_lshl_add_u64 v[48:49], v[0:1], 0, v[48:49]
	v_lshlrev_b64 v[50:51], 12, v[50:51]
	v_lshlrev_b64 v[52:53], 12, v[52:53]
	v_lshl_add_u64 v[50:51], v[0:1], 0, v[50:51]
	v_lshl_add_u64 v[52:53], v[0:1], 0, v[52:53]
	global_load_dword v240, v[46:47], off
	global_load_dword v240, v[48:49], off
	global_load_dword v240, v[50:51], off
	global_load_dword v240, v[52:53], off
	v_or_b32_e32 v46, s8, v12
	v_or_b32_e32 v48, s8, v13
	v_ashrrev_i32_e32 v47, 31, v46
	v_ashrrev_i32_e32 v49, 31, v48
	v_or_b32_e32 v50, s8, v14
	v_or_b32_e32 v52, s8, v15
	v_lshlrev_b64 v[46:47], 12, v[46:47]
	v_lshlrev_b64 v[48:49], 12, v[48:49]
	v_ashrrev_i32_e32 v51, 31, v50
	v_ashrrev_i32_e32 v53, 31, v52
	v_lshl_add_u64 v[46:47], v[0:1], 0, v[46:47]
	v_lshl_add_u64 v[48:49], v[0:1], 0, v[48:49]
	v_lshlrev_b64 v[50:51], 12, v[50:51]
	v_lshlrev_b64 v[52:53], 12, v[52:53]
	v_lshl_add_u64 v[50:51], v[0:1], 0, v[50:51]
	v_lshl_add_u64 v[52:53], v[0:1], 0, v[52:53]
	global_load_dword v240, v[46:47], off
	global_load_dword v240, v[48:49], off
	global_load_dword v240, v[50:51], off
	global_load_dword v240, v[52:53], off
	v_or_b32_e32 v48, s8, v16
	v_or_b32_e32 v50, s8, v17
	v_ashrrev_i32_e32 v49, 31, v48
	v_ashrrev_i32_e32 v51, 31, v50
	v_or_b32_e32 v52, s8, v18
	v_or_b32_e32 v54, s8, v19
	v_lshlrev_b64 v[48:49], 12, v[48:49]
	v_lshlrev_b64 v[50:51], 12, v[50:51]
	v_ashrrev_i32_e32 v53, 31, v52
	v_ashrrev_i32_e32 v55, 31, v54
	v_lshl_add_u64 v[48:49], v[0:1], 0, v[48:49]
	v_lshl_add_u64 v[50:51], v[0:1], 0, v[50:51]
	v_lshlrev_b64 v[52:53], 12, v[52:53]
	v_lshlrev_b64 v[54:55], 12, v[54:55]
	v_lshl_add_u64 v[52:53], v[0:1], 0, v[52:53]
	v_lshl_add_u64 v[54:55], v[0:1], 0, v[54:55]
	global_load_dword v240, v[48:49], off
	global_load_dword v240, v[50:51], off
	global_load_dword v240, v[52:53], off
	global_load_dword v240, v[54:55], off
	v_or_b32_e32 v48, s8, v20
	v_or_b32_e32 v50, s8, v21
	v_ashrrev_i32_e32 v49, 31, v48
	v_ashrrev_i32_e32 v51, 31, v50
	v_or_b32_e32 v52, s8, v22
	v_or_b32_e32 v54, s8, v23
	v_lshlrev_b64 v[48:49], 12, v[48:49]
	v_lshlrev_b64 v[50:51], 12, v[50:51]
	v_ashrrev_i32_e32 v53, 31, v52
	v_ashrrev_i32_e32 v55, 31, v54
	v_lshl_add_u64 v[48:49], v[0:1], 0, v[48:49]
	v_lshl_add_u64 v[50:51], v[0:1], 0, v[50:51]
	v_lshlrev_b64 v[52:53], 12, v[52:53]
	v_lshlrev_b64 v[54:55], 12, v[54:55]
	v_lshl_add_u64 v[52:53], v[0:1], 0, v[52:53]
	v_lshl_add_u64 v[54:55], v[0:1], 0, v[54:55]
	global_load_dword v240, v[48:49], off
	global_load_dword v240, v[50:51], off
	global_load_dword v240, v[52:53], off
	global_load_dword v240, v[54:55], off
	v_or_b32_e32 v48, s8, v24
	v_or_b32_e32 v50, s8, v25
	v_ashrrev_i32_e32 v49, 31, v48
	v_ashrrev_i32_e32 v51, 31, v50
	v_or_b32_e32 v52, s8, v26
	v_or_b32_e32 v54, s8, v27
	v_lshlrev_b64 v[48:49], 12, v[48:49]
	v_lshlrev_b64 v[50:51], 12, v[50:51]
	v_ashrrev_i32_e32 v53, 31, v52
	v_ashrrev_i32_e32 v55, 31, v54
	v_lshl_add_u64 v[48:49], v[0:1], 0, v[48:49]
	v_lshl_add_u64 v[50:51], v[0:1], 0, v[50:51]
	v_lshlrev_b64 v[52:53], 12, v[52:53]
	v_lshlrev_b64 v[54:55], 12, v[54:55]
	v_lshl_add_u64 v[52:53], v[0:1], 0, v[52:53]
	v_lshl_add_u64 v[54:55], v[0:1], 0, v[54:55]
	global_load_dword v240, v[48:49], off
	global_load_dword v240, v[50:51], off
	global_load_dword v240, v[52:53], off
	global_load_dword v240, v[54:55], off
	v_or_b32_e32 v48, s8, v28
	v_or_b32_e32 v50, s8, v29
	v_ashrrev_i32_e32 v49, 31, v48
	v_ashrrev_i32_e32 v51, 31, v50
	v_or_b32_e32 v52, s8, v30
	v_or_b32_e32 v54, s8, v31
	v_lshlrev_b64 v[48:49], 12, v[48:49]
	v_lshlrev_b64 v[50:51], 12, v[50:51]
	v_ashrrev_i32_e32 v53, 31, v52
	v_ashrrev_i32_e32 v55, 31, v54
	v_lshl_add_u64 v[48:49], v[0:1], 0, v[48:49]
	v_lshl_add_u64 v[50:51], v[0:1], 0, v[50:51]
	v_lshlrev_b64 v[52:53], 12, v[52:53]
	v_lshlrev_b64 v[54:55], 12, v[54:55]
	v_lshl_add_u64 v[52:53], v[0:1], 0, v[52:53]
	v_lshl_add_u64 v[54:55], v[0:1], 0, v[54:55]
	global_load_dword v240, v[48:49], off
	global_load_dword v240, v[50:51], off
	global_load_dword v240, v[52:53], off
	global_load_dword v240, v[54:55], off
	v_or_b32_e32 v48, s8, v32
	v_or_b32_e32 v50, s8, v33
	v_ashrrev_i32_e32 v49, 31, v48
	v_ashrrev_i32_e32 v51, 31, v50
	v_or_b32_e32 v52, s8, v34
	v_or_b32_e32 v54, s8, v35
	v_lshlrev_b64 v[48:49], 12, v[48:49]
	v_lshlrev_b64 v[50:51], 12, v[50:51]
	v_ashrrev_i32_e32 v53, 31, v52
	v_ashrrev_i32_e32 v55, 31, v54
	v_lshl_add_u64 v[48:49], v[0:1], 0, v[48:49]
	v_lshl_add_u64 v[50:51], v[0:1], 0, v[50:51]
	v_lshlrev_b64 v[52:53], 12, v[52:53]
	v_lshlrev_b64 v[54:55], 12, v[54:55]
	v_lshl_add_u64 v[52:53], v[0:1], 0, v[52:53]
	v_lshl_add_u64 v[54:55], v[0:1], 0, v[54:55]
	global_load_dword v240, v[48:49], off
	global_load_dword v240, v[50:51], off
	global_load_dword v240, v[52:53], off
	global_load_dword v240, v[54:55], off
	v_or_b32_e32 v46, s8, v3
	v_or_b32_e32 v48, s8, v4
	v_ashrrev_i32_e32 v47, 31, v46
	v_ashrrev_i32_e32 v49, 31, v48
	v_or_b32_e32 v50, s8, v5
	v_or_b32_e32 v52, s8, v7
	v_lshlrev_b64 v[46:47], 12, v[46:47]
	v_lshlrev_b64 v[48:49], 12, v[48:49]
	v_ashrrev_i32_e32 v51, 31, v50
	v_ashrrev_i32_e32 v53, 31, v52
	v_lshl_add_u64 v[46:47], v[0:1], 0, v[46:47]
	v_lshl_add_u64 v[48:49], v[0:1], 0, v[48:49]
	v_lshlrev_b64 v[50:51], 12, v[50:51]
	v_lshlrev_b64 v[52:53], 12, v[52:53]
	v_lshl_add_u64 v[50:51], v[0:1], 0, v[50:51]
	v_lshl_add_u64 v[52:53], v[0:1], 0, v[52:53]
	global_load_dword v54, v[46:47], off
	s_nop 0
	global_load_dword v48, v[48:49], off
	s_nop 0
	global_load_dword v46, v[50:51], off
	global_load_dword v47, v[52:53], off
	s_waitcnt vmcnt(2)
	ds_write2_b32 v43, v54, v48 offset1:66

; __device__ __forceinline__ void transpose_item(const float* W, int K, int Nsrc, bf16_t* WT, int dst_n0, int src_n0, int nvalid, const float* kgain, int k0, LAS float* scr, int lane) {
;     ...
; #pragma unroll 32
;     for (int i = 0; i < 32; ++i) { const int kk = 2 * i + (lane >> 5);
;         float v = (srcn < nvalid) ? W[(size_t)(k0 + kk) * Nsrc + srcn] : 0.f;
;         if (kgain) v *= kgain[k0 + kk];
;         scr[kk * 33 + (lane & 31)] = v; }
; __device__ __forceinline__ void convert_group(const Frame& F, const float* W, int nl, int K, int Nsrc, int Ndst, bf16_t* WT, int kind, const float* kgain, int gain_stride) {
;     ...
;     for (int it = F.gw; it < total; it += F.NGW) {
;         const int l = it / per, r = it % per, kb = r / nblk, nb = r % nblk, dn0 = nb * 32;
;         int sn0 = dn0;
;         if (kind == 1) { const int j = dn0 >> 8, i0 = dn0 & 255; sn0 = (i0 < 128) ? (128 * j + i0) : (D_FF + 128 * j + i0 - 128); }
;         transpose_item(W + (size_t)l * K * Nsrc, K, Nsrc, WT + (size_t)l * Ndst * K, dn0, sn0, Nsrc, kgain ? kgain + l * gain_stride : nullptr, kb * 64, scr, lane_l);
.LBB0_1047:
	s_mul_hi_i32 s6, s16, 0x2e8ba2e9
	s_lshr_b32 s7, s6, 31
	s_ashr_i32 s6, s6, 9
	s_add_i32 s6, s6, s7
	s_mul_i32 s7, s6, 0xfffff500
	s_add_i32 s7, s16, s7
	s_mul_i32 s8, s7, 0xba3
	s_lshr_b32 s9, s8, 31
	s_ashr_i32 s18, s8, 19
	s_add_i32 s18, s18, s9
	s_mul_i32 s8, s18, 0xb0
	s_sub_i32 s7, s7, s8
	s_sext_i32_i16 s7, s7
	s_lshl_b32 s17, s7, 5
	s_lshl_b32 s7, s7, 4
	s_and_b32 s8, s17, 0xe0
	s_and_b32 s7, s7, 0xffffff80
	s_or_b32 s9, s7, s8
	s_add_i32 s7, s7, s8
	s_addk_i32 s7, 0xa80
	s_cmpk_lt_u32 s8, 0x80
	s_cselect_b32 s10, s9, s7
	s_mul_hi_i32 s9, s6, 0x580000
	s_mul_i32 s8, s6, 0x580000
	s_lshl_b64 s[6:7], s[8:9], 2
	s_add_u32 s12, s4, s6
	v_or_b32_e32 v0, s10, v2
	s_movk_i32 s6, 0x15ff
	s_addc_u32 s13, s5, s7
	v_cmp_lt_i32_e32 vcc, s6, v0
	s_and_saveexec_b64 s[6:7], vcc
	s_xor_b64 s[6:7], exec, s[6:7]
	ds_write2_b32 v43, v165, v165 offset1:66
	s_or_saveexec_b64 s[10:11], s[6:7]
	v_ashrrev_i32_e32 v1, 31, v0
	s_lshl_b32 s6, s18, 6
	v_lshl_add_u64 v[0:1], v[0:1], 2, s[12:13]
	v_mov_b32_e32 v46, 0
	v_mov_b32_e32 v47, 0
	s_xor_b64 exec, exec, s[10:11]
	s_cbranch_execz .LBB0_1051
	v_or_b32_e32 v46, s6, v8
	v_or_b32_e32 v48, s6, v9
	v_mul_i32_i24_e32 v46, 0x1600, v46
	v_mul_i32_i24_e32 v48, 0x1600, v48
	v_or_b32_e32 v50, s6, v10
	v_or_b32_e32 v52, s6, v11
	v_ashrrev_i32_e32 v47, 31, v46
	v_ashrrev_i32_e32 v49, 31, v48
	v_mul_i32_i24_e32 v50, 0x1600, v50
	v_mul_i32_i24_e32 v52, 0x1600, v52
	v_lshl_add_u64 v[46:47], v[46:47], 2, v[0:1]
	v_lshl_add_u64 v[48:49], v[48:49], 2, v[0:1]
	v_ashrrev_i32_e32 v51, 31, v50
	v_ashrrev_i32_e32 v53, 31, v52
	v_lshl_add_u64 v[50:51], v[50:51], 2, v[0:1]
	v_lshl_add_u64 v[52:53], v[52:53], 2, v[0:1]
	global_load_dword v240, v[46:47], off
	global_load_dword v240, v[48:49], off
	global_load_dword v240, v[50:51], off
	global_load_dword v240, v[52:53], off
	v_or_b32_e32 v46, s6, v12
	v_or_b32_e32 v48, s6, v13
	v_mul_i32_i24_e32 v46, 0x1600, v46
	v_mul_i32_i24_e32 v48, 0x1600, v48
	v_or_b32_e32 v50, s6, v14
	v_or_b32_e32 v52, s6, v15
	v_ashrrev_i32_e32 v47, 31, v46
	v_ashrrev_i32_e32 v49, 31, v48
	v_mul_i32_i24_e32 v50, 0x1600, v50
	v_mul_i32_i24_e32 v52, 0x1600, v52
	v_lshl_add_u64 v[46:47], v[46:47], 2, v[0:1]
	v_lshl_add_u64 v[48:49], v[48:49], 2, v[0:1]
	v_ashrrev_i32_e32 v51, 31, v50
	v_ashrrev_i32_e32 v53, 31, v52
	v_lshl_add_u64 v[50:51], v[50:51], 2, v[0:1]
	v_lshl_add_u64 v[52:53], v[52:53], 2, v[0:1]
	global_load_dword v240, v[46:47], off
	global_load_dword v240, v[48:49], off
	global_load_dword v240, v[50:51], off
	global_load_dword v240, v[52:53], off
	v_or_b32_e32 v47, s6, v16
	v_mul_i32_i24_e32 v48, 0x1600, v47
	v_or_b32_e32 v47, s6, v17
	v_mul_i32_i24_e32 v50, 0x1600, v47
	v_or_b32_e32 v47, s6, v18
	v_mul_i32_i24_e32 v52, 0x1600, v47
	v_or_b32_e32 v47, s6, v19
	v_ashrrev_i32_e32 v49, 31, v48
	v_ashrrev_i32_e32 v51, 31, v50
	v_mul_i32_i24_e32 v54, 0x1600, v47
	v_lshl_add_u64 v[48:49], v[48:49], 2, v[0:1]
	v_lshl_add_u64 v[50:51], v[50:51], 2, v[0:1]
	v_ashrrev_i32_e32 v53, 31, v52
	v_ashrrev_i32_e32 v55, 31, v54
	v_lshl_add_u64 v[52:53], v[52:53], 2, v[0:1]
	v_lshl_add_u64 v[54:55], v[54:55], 2, v[0:1]
	global_load_dword v240, v[48:49], off
	global_load_dword v240, v[50:51], off
	global_load_dword v240, v[52:53], off
	global_load_dword v240, v[54:55], off
	v_or_b32_e32 v47, s6, v20
	v_mul_i32_i24_e32 v48, 0x1600, v47
	v_or_b32_e32 v47, s6, v21
	v_mul_i32_i24_e32 v50, 0x1600, v47
	v_or_b32_e32 v47, s6, v22
	v_mul_i32_i24_e32 v52, 0x1600, v47
	v_or_b32_e32 v47, s6, v23
	v_ashrrev_i32_e32 v49, 31, v48
	v_ashrrev_i32_e32 v51, 31, v50
	v_mul_i32_i24_e32 v54, 0x1600, v47
	v_lshl_add_u64 v[48:49], v[48:49], 2, v[0:1]
	v_lshl_add_u64 v[50:51], v[50:51], 2, v[0:1]
	v_ashrrev_i32_e32 v53, 31, v52
	v_ashrrev_i32_e32 v55, 31, v54
	v_lshl_add_u64 v[52:53], v[52:53], 2, v[0:1]
	v_lshl_add_u64 v[54:55], v[54:55], 2, v[0:1]
	global_load_dword v240, v[48:49], off
	global_load_dword v240, v[50:51], off
	global_load_dword v240, v[52:53], off
	global_load_dword v240, v[54:55], off
	v_or_b32_e32 v47, s6, v24
	v_mul_i32_i24_e32 v48, 0x1600, v47
	v_or_b32_e32 v47, s6, v25
	v_mul_i32_i24_e32 v50, 0x1600, v47
	v_or_b32_e32 v47, s6, v26
	v_mul_i32_i24_e32 v52, 0x1600, v47
	v_or_b32_e32 v47, s6, v27
	v_ashrrev_i32_e32 v49, 31, v48
	v_ashrrev_i32_e32 v51, 31, v50
	v_mul_i32_i24_e32 v54, 0x1600, v47
	v_lshl_add_u64 v[48:49], v[48:49], 2, v[0:1]
	v_lshl_add_u64 v[50:51], v[50:51], 2, v[0:1]
	v_ashrrev_i32_e32 v53, 31, v52
	v_ashrrev_i32_e32 v55, 31, v54
	v_lshl_add_u64 v[52:53], v[52:53], 2, v[0:1]
	v_lshl_add_u64 v[54:55], v[54:55], 2, v[0:1]
	global_load_dword v240, v[48:49], off
	global_load_dword v240, v[50:51], off
	global_load_dword v240, v[52:53], off
	global_load_dword v240, v[54:55], off
	v_or_b32_e32 v47, s6, v28
	v_mul_i32_i24_e32 v48, 0x1600, v47
	v_or_b32_e32 v47, s6, v29
	v_mul_i32_i24_e32 v50, 0x1600, v47
	v_or_b32_e32 v47, s6, v30
	v_mul_i32_i24_e32 v52, 0x1600, v47
	v_or_b32_e32 v47, s6, v31
	v_ashrrev_i32_e32 v49, 31, v48
	v_ashrrev_i32_e32 v51, 31, v50
	v_mul_i32_i24_e32 v54, 0x1600, v47
	v_lshl_add_u64 v[48:49], v[48:49], 2, v[0:1]
	v_lshl_add_u64 v[50:51], v[50:51], 2, v[0:1]
	v_ashrrev_i32_e32 v53, 31, v52
	v_ashrrev_i32_e32 v55, 31, v54
	v_lshl_add_u64 v[52:53], v[52:53], 2, v[0:1]
	v_lshl_add_u64 v[54:55], v[54:55], 2, v[0:1]
	global_load_dword v240, v[48:49], off
	global_load_dword v240, v[50:51], off
	global_load_dword v240, v[52:53], off
	global_load_dword v240, v[54:55], off
	v_or_b32_e32 v47, s6, v32
	v_mul_i32_i24_e32 v48, 0x1600, v47
	v_or_b32_e32 v47, s6, v33
	v_mul_i32_i24_e32 v50, 0x1600, v47
	v_or_b32_e32 v47, s6, v34
	v_mul_i32_i24_e32 v52, 0x1600, v47
	v_or_b32_e32 v47, s6, v35
	v_ashrrev_i32_e32 v49, 31, v48
	v_ashrrev_i32_e32 v51, 31, v50
	v_mul_i32_i24_e32 v54, 0x1600, v47
	v_lshl_add_u64 v[48:49], v[48:49], 2, v[0:1]
	v_lshl_add_u64 v[50:51], v[50:51], 2, v[0:1]
	v_ashrrev_i32_e32 v53, 31, v52
	v_ashrrev_i32_e32 v55, 31, v54
	v_lshl_add_u64 v[52:53], v[52:53], 2, v[0:1]
	v_lshl_add_u64 v[54:55], v[54:55], 2, v[0:1]
	global_load_dword v240, v[48:49], off
	global_load_dword v240, v[50:51], off
	global_load_dword v240, v[52:53], off
	global_load_dword v240, v[54:55], off
	v_or_b32_e32 v46, s6, v3
	v_or_b32_e32 v48, s6, v4
	v_mul_i32_i24_e32 v46, 0x1600, v46
	v_mul_i32_i24_e32 v48, 0x1600, v48
	v_or_b32_e32 v50, s6, v5
	v_or_b32_e32 v52, s6, v7
	v_ashrrev_i32_e32 v47, 31, v46
	v_ashrrev_i32_e32 v49, 31, v48
	v_mul_i32_i24_e32 v50, 0x1600, v50
	v_mul_i32_i24_e32 v52, 0x1600, v52
	v_lshl_add_u64 v[46:47], v[46:47], 2, v[0:1]
	v_lshl_add_u64 v[48:49], v[48:49], 2, v[0:1]
	v_ashrrev_i32_e32 v51, 31, v50
	v_ashrrev_i32_e32 v53, 31, v52
	v_lshl_add_u64 v[50:51], v[50:51], 2, v[0:1]
	v_lshl_add_u64 v[52:53], v[52:53], 2, v[0:1]
	global_load_dword v54, v[46:47], off
	s_nop 0
	global_load_dword v48, v[48:49], off
	s_nop 0
	global_load_dword v46, v[50:51], off
	global_load_dword v47, v[52:53], off
	s_waitcnt vmcnt(2)
	ds_write2_b32 v43, v54, v48 offset1:66

; __device__ __forceinline__ void transpose_item(const float* W, int K, int Nsrc, bf16_t* WT, int dst_n0, int src_n0, int nvalid, const float* kgain, int k0, LAS float* scr, int lane) {
;     ...
; #pragma unroll 32
;     for (int i = 0; i < 32; ++i) { const int kk = 2 * i + (lane >> 5);
;         float v = (srcn < nvalid) ? W[(size_t)(k0 + kk) * Nsrc + srcn] : 0.f;
;         if (kgain) v *= kgain[k0 + kk];
;         scr[kk * 33 + (lane & 31)] = v; }
; __device__ __forceinline__ void convert_group(const Frame& F, const float* W, int nl, int K, int Nsrc, int Ndst, bf16_t* WT, int kind, const float* kgain, int gain_stride) {
;     ...
;     for (int it = F.gw; it < total; it += F.NGW) {
;         const int l = it / per, r = it % per, kb = r / nblk, nb = r % nblk, dn0 = nb * 32;
;         int sn0 = dn0;
;         if (kind == 1) { const int j = dn0 >> 8, i0 = dn0 & 255; sn0 = (i0 < 128) ? (128 * j + i0) : (D_FF + 128 * j + i0 - 128); }
;         transpose_item(W + (size_t)l * K * Nsrc, K, Nsrc, WT + (size_t)l * Ndst * K, dn0, sn0, Nsrc, kgain ? kgain + l * gain_stride : nullptr, kb * 64, scr, lane_l);
.LBB0_1083:
	s_mul_hi_i32 s6, s8, 0x2e8ba2e9
	s_lshr_b32 s7, s6, 31
	s_ashr_i32 s6, s6, 8
	s_add_i32 s6, s6, s7
	s_mul_i32 s7, s6, 0xfffffa80
	s_add_i32 s7, s8, s7
	s_mov_b32 s18, s8
	s_bfe_u32 s8, s7, 0x5001a
	s_add_i32 s17, s7, s8
	s_and_b32 s8, s17, 0xffe0
	s_sub_i32 s7, s7, s8
	s_sext_i32_i16 s7, s7
	s_lshl_b32 s16, s7, 5
	s_mul_hi_i32 s7, s6, 0x2c0000
	s_mul_i32 s6, s6, 0x2c0000
	s_lshl_b64 s[8:9], s[6:7], 2
	s_add_u32 s12, s4, s8
	v_or_b32_e32 v0, s16, v2
	s_addc_u32 s13, s5, s9
	v_cmp_lt_i32_e32 vcc, s48, v0
	s_and_saveexec_b64 s[8:9], vcc
	s_xor_b64 s[8:9], exec, s[8:9]
	ds_write2_b32 v43, v165, v165 offset1:66
	s_or_saveexec_b64 s[10:11], s[8:9]
	s_sext_i32_i16 s8, s17
	s_lshl_b32 s8, s8, 1
	v_ashrrev_i32_e32 v1, 31, v0
	s_andn2_b32 s8, s8, 63
	v_lshl_add_u64 v[0:1], v[0:1], 2, s[12:13]
	v_mov_b32_e32 v46, 0
	v_mov_b32_e32 v47, 0
	s_xor_b64 exec, exec, s[10:11]
	s_cbranch_execz .LBB0_1087
	v_or_b32_e32 v46, s8, v8
	v_or_b32_e32 v48, s8, v9
	v_ashrrev_i32_e32 v47, 31, v46
	v_ashrrev_i32_e32 v49, 31, v48
	v_or_b32_e32 v50, s8, v10
	v_or_b32_e32 v52, s8, v11
	v_lshlrev_b64 v[46:47], 12, v[46:47]
	v_lshlrev_b64 v[48:49], 12, v[48:49]
	v_ashrrev_i32_e32 v51, 31, v50
	v_ashrrev_i32_e32 v53, 31, v52
	v_lshl_add_u64 v[46:47], v[0:1], 0, v[46:47]
	v_lshl_add_u64 v[48:49], v[0:1], 0, v[48:49]
	v_lshlrev_b64 v[50:51], 12, v[50:51]
	v_lshlrev_b64 v[52:53], 12, v[52:53]
	v_lshl_add_u64 v[50:51], v[0:1], 0, v[50:51]
	v_lshl_add_u64 v[52:53], v[0:1], 0, v[52:53]
	global_load_dword v240, v[46:47], off
	global_load_dword v240, v[48:49], off
	global_load_dword v240, v[50:51], off
	global_load_dword v240, v[52:53], off
	v_or_b32_e32 v46, s8, v12
	v_or_b32_e32 v48, s8, v13
	v_ashrrev_i32_e32 v47, 31, v46
	v_ashrrev_i32_e32 v49, 31, v48
	v_or_b32_e32 v50, s8, v14
	v_or_b32_e32 v52, s8, v15
	v_lshlrev_b64 v[46:47], 12, v[46:47]
	v_lshlrev_b64 v[48:49], 12, v[48:49]
	v_ashrrev_i32_e32 v51, 31, v50
	v_ashrrev_i32_e32 v53, 31, v52
	v_lshl_add_u64 v[46:47], v[0:1], 0, v[46:47]
	v_lshl_add_u64 v[48:49], v[0:1], 0, v[48:49]
	v_lshlrev_b64 v[50:51], 12, v[50:51]
	v_lshlrev_b64 v[52:53], 12, v[52:53]
	v_lshl_add_u64 v[50:51], v[0:1], 0, v[50:51]
	v_lshl_add_u64 v[52:53], v[0:1], 0, v[52:53]
	global_load_dword v240, v[46:47], off
	global_load_dword v240, v[48:49], off
	global_load_dword v240, v[50:51], off
	global_load_dword v240, v[52:53], off
	v_or_b32_e32 v48, s8, v16
	v_or_b32_e32 v50, s8, v17
	v_ashrrev_i32_e32 v49, 31, v48
	v_ashrrev_i32_e32 v51, 31, v50
	v_or_b32_e32 v52, s8, v18
	v_or_b32_e32 v54, s8, v19
	v_lshlrev_b64 v[48:49], 12, v[48:49]
	v_lshlrev_b64 v[50:51], 12, v[50:51]
	v_ashrrev_i32_e32 v53, 31, v52
	v_ashrrev_i32_e32 v55, 31, v54
	v_lshl_add_u64 v[48:49], v[0:1], 0, v[48:49]
	v_lshl_add_u64 v[50:51], v[0:1], 0, v[50:51]
	v_lshlrev_b64 v[52:53], 12, v[52:53]
	v_lshlrev_b64 v[54:55], 12, v[54:55]
	v_lshl_add_u64 v[52:53], v[0:1], 0, v[52:53]
	v_lshl_add_u64 v[54:55], v[0:1], 0, v[54:55]
	global_load_dword v240, v[48:49], off
	global_load_dword v240, v[50:51], off
	global_load_dword v240, v[52:53], off
	global_load_dword v240, v[54:55], off
	v_or_b32_e32 v48, s8, v20
	v_or_b32_e32 v50, s8, v21
	v_ashrrev_i32_e32 v49, 31, v48
	v_ashrrev_i32_e32 v51, 31, v50
	v_or_b32_e32 v52, s8, v22
	v_or_b32_e32 v54, s8, v23
	v_lshlrev_b64 v[48:49], 12, v[48:49]
	v_lshlrev_b64 v[50:51], 12, v[50:51]
	v_ashrrev_i32_e32 v53, 31, v52
	v_ashrrev_i32_e32 v55, 31, v54
	v_lshl_add_u64 v[48:49], v[0:1], 0, v[48:49]
	v_lshl_add_u64 v[50:51], v[0:1], 0, v[50:51]
	v_lshlrev_b64 v[52:53], 12, v[52:53]
	v_lshlrev_b64 v[54:55], 12, v[54:55]
	v_lshl_add_u64 v[52:53], v[0:1], 0, v[52:53]
	v_lshl_add_u64 v[54:55], v[0:1], 0, v[54:55]
	global_load_dword v240, v[48:49], off
	global_load_dword v240, v[50:51], off
	global_load_dword v240, v[52:53], off
	global_load_dword v240, v[54:55], off
	v_or_b32_e32 v48, s8, v24
	v_or_b32_e32 v50, s8, v25
	v_ashrrev_i32_e32 v49, 31, v48
	v_ashrrev_i32_e32 v51, 31, v50
	v_or_b32_e32 v52, s8, v26
	v_or_b32_e32 v54, s8, v27
	v_lshlrev_b64 v[48:49], 12, v[48:49]
	v_lshlrev_b64 v[50:51], 12, v[50:51]
	v_ashrrev_i32_e32 v53, 31, v52
	v_ashrrev_i32_e32 v55, 31, v54
	v_lshl_add_u64 v[48:49], v[0:1], 0, v[48:49]
	v_lshl_add_u64 v[50:51], v[0:1], 0, v[50:51]
	v_lshlrev_b64 v[52:53], 12, v[52:53]
	v_lshlrev_b64 v[54:55], 12, v[54:55]
	v_lshl_add_u64 v[52:53], v[0:1], 0, v[52:53]
	v_lshl_add_u64 v[54:55], v[0:1], 0, v[54:55]
	global_load_dword v240, v[48:49], off
	global_load_dword v240, v[50:51], off
	global_load_dword v240, v[52:53], off
	global_load_dword v240, v[54:55], off
	v_or_b32_e32 v48, s8, v28
	v_or_b32_e32 v50, s8, v29
	v_ashrrev_i32_e32 v49, 31, v48
	v_ashrrev_i32_e32 v51, 31, v50
	v_or_b32_e32 v52, s8, v30
	v_or_b32_e32 v54, s8, v31
	v_lshlrev_b64 v[48:49], 12, v[48:49]
	v_lshlrev_b64 v[50:51], 12, v[50:51]
	v_ashrrev_i32_e32 v53, 31, v52
	v_ashrrev_i32_e32 v55, 31, v54
	v_lshl_add_u64 v[48:49], v[0:1], 0, v[48:49]
	v_lshl_add_u64 v[50:51], v[0:1], 0, v[50:51]
	v_lshlrev_b64 v[52:53], 12, v[52:53]
	v_lshlrev_b64 v[54:55], 12, v[54:55]
	v_lshl_add_u64 v[52:53], v[0:1], 0, v[52:53]
	v_lshl_add_u64 v[54:55], v[0:1], 0, v[54:55]
	global_load_dword v240, v[48:49], off
	global_load_dword v240, v[50:51], off
	global_load_dword v240, v[52:53], off
	global_load_dword v240, v[54:55], off
	v_or_b32_e32 v48, s8, v32
	v_or_b32_e32 v50, s8, v33
	v_ashrrev_i32_e32 v49, 31, v48
	v_ashrrev_i32_e32 v51, 31, v50
	v_or_b32_e32 v52, s8, v34
	v_or_b32_e32 v54, s8, v35
	v_lshlrev_b64 v[48:49], 12, v[48:49]
	v_lshlrev_b64 v[50:51], 12, v[50:51]
	v_ashrrev_i32_e32 v53, 31, v52
	v_ashrrev_i32_e32 v55, 31, v54
	v_lshl_add_u64 v[48:49], v[0:1], 0, v[48:49]
	v_lshl_add_u64 v[50:51], v[0:1], 0, v[50:51]
	v_lshlrev_b64 v[52:53], 12, v[52:53]
	v_lshlrev_b64 v[54:55], 12, v[54:55]
	v_lshl_add_u64 v[52:53], v[0:1], 0, v[52:53]
	v_lshl_add_u64 v[54:55], v[0:1], 0, v[54:55]
	global_load_dword v240, v[48:49], off
	global_load_dword v240, v[50:51], off
	global_load_dword v240, v[52:53], off
	global_load_dword v240, v[54:55], off
	v_or_b32_e32 v46, s8, v3
	v_or_b32_e32 v48, s8, v4
	v_ashrrev_i32_e32 v47, 31, v46
	v_ashrrev_i32_e32 v49, 31, v48
	v_or_b32_e32 v50, s8, v5
	v_or_b32_e32 v52, s8, v7
	v_lshlrev_b64 v[46:47], 12, v[46:47]
	v_lshlrev_b64 v[48:49], 12, v[48:49]
	v_ashrrev_i32_e32 v51, 31, v50
	v_ashrrev_i32_e32 v53, 31, v52
	v_lshl_add_u64 v[46:47], v[0:1], 0, v[46:47]
	v_lshl_add_u64 v[48:49], v[0:1], 0, v[48:49]
	v_lshlrev_b64 v[50:51], 12, v[50:51]
	v_lshlrev_b64 v[52:53], 12, v[52:53]
	v_lshl_add_u64 v[50:51], v[0:1], 0, v[50:51]
	v_lshl_add_u64 v[52:53], v[0:1], 0, v[52:53]
	global_load_dword v54, v[46:47], off
	s_nop 0
	global_load_dword v48, v[48:49], off
	s_nop 0
	global_load_dword v46, v[50:51], off
	global_load_dword v47, v[52:53], off
	s_waitcnt vmcnt(2)
	ds_write2_b32 v43, v54, v48 offset1:66
